# selected-branch constant-bias tiles: when both column blocks are active their softmax instruction streams are interleaved 1:1 (independent chains) to hide VALU/trans latencies
# speedup vs baseline: 1.0148x; 1.0148x over previous
.LBB0_439:
	s_andn2_b64 vcc, exec, s[6:7]
	s_cbranch_vccnz .LBB0_448
	v_and_b32_e32 v0, 1, v164
	v_cmp_eq_u32_e64 s[42:43], 1, v0
	v_and_b32_e32 v0, 1, v162
	v_cmp_eq_u32_e64 s[44:45], 1, v0
	s_or_b64 s[6:7], s[44:45], s[42:43]
	v_cndmask_b32_e64 v54, 0, 1, s[6:7]
	v_cmp_ne_u32_e32 vcc, 0, v54
	s_cbranch_vccz .Lsel_fast
	v_add_u32_e32 v54, s13, v196
	v_add_u32_e32 v62, v54, v194
	v_add_u32_e32 v0, v54, v195
	s_cmp_lg_u64 s[44:45], 0
	ds_read_b128 v[64:67], v62 offset:16384
	ds_read_b128 v[54:57], v0 offset:16384
	ds_read_b128 v[68:71], v62 offset:18432
	ds_read_b128 v[58:61], v0 offset:18432
	ds_read_b128 v[72:75], v62 offset:20480
	ds_read_b128 v[76:79], v0 offset:20480
	ds_read_b128 v[80:83], v62 offset:22528
	ds_read_b128 v[84:87], v0 offset:22528
	ds_read_b32 v188, v193
	s_waitcnt lgkmcnt(0)
	s_cbranch_scc0 .Lp2v_m1
	s_cmp_lg_u64 s[42:43], 0
	s_cbranch_scc0 .Lp2v_only0
	s_setprio 1
	v_mfma_f32_16x16x32_bf16 v[170:173], v[64:67], v[2:5], 0
	v_mfma_f32_16x16x32_bf16 v[174:177], v[68:71], v[2:5], 0
	v_mfma_f32_16x16x32_bf16 v[170:173], v[54:57], v[6:9], v[170:173]
	v_mfma_f32_16x16x32_bf16 v[178:181], v[72:75], v[2:5], 0
	v_mfma_f32_16x16x32_bf16 v[174:177], v[58:61], v[6:9], v[174:177]
	v_mfma_f32_16x16x32_bf16 v[182:185], v[80:83], v[2:5], 0
	v_mfma_f32_16x16x32_bf16 v[178:181], v[76:79], v[6:9], v[178:181]
	v_mfma_f32_16x16x32_bf16 v[182:185], v[84:87], v[6:9], v[182:185]
	v_mfma_f32_16x16x32_bf16 v[64:67], v[64:67], v[10:13], 0
	v_mfma_f32_16x16x32_bf16 v[68:71], v[68:71], v[10:13], 0
	v_mfma_f32_16x16x32_bf16 v[64:67], v[54:57], v[14:17], v[64:67]
	v_mfma_f32_16x16x32_bf16 v[72:75], v[72:75], v[10:13], 0
	v_mfma_f32_16x16x32_bf16 v[68:71], v[58:61], v[14:17], v[68:71]
	v_mfma_f32_16x16x32_bf16 v[80:83], v[80:83], v[10:13], 0
	v_mfma_f32_16x16x32_bf16 v[72:75], v[76:79], v[14:17], v[72:75]
	v_mfma_f32_16x16x32_bf16 v[80:83], v[84:87], v[14:17], v[80:83]
	s_setprio 0
	s_nop 7
	v_max3_f32 v186, v170, v171, v172
	v_max3_f32 v76, v64, v65, v66
	v_max3_f32 v186, v186, v173, v174
	v_max3_f32 v76, v76, v67, v68
	v_max3_f32 v186, v186, v175, v176
	v_max3_f32 v76, v76, v69, v70
	v_max3_f32 v186, v186, v177, v178
	v_max3_f32 v76, v76, v71, v72
	v_max3_f32 v186, v186, v179, v180
	v_max3_f32 v76, v76, v73, v74
	v_max3_f32 v186, v186, v181, v182
	v_max3_f32 v76, v76, v75, v80
	v_max3_f32 v186, v186, v183, v184
	v_max3_f32 v76, v76, v81, v82
	v_max_f32_e32 v186, v186, v185
	v_max_f32_e32 v76, v76, v83
	v_mov_b32_e32 v187, v186
	v_mov_b32_e32 v77, v76
	s_nop 1
	s_nop 1
	v_permlane16_swap_b32_e32 v186, v187
	v_permlane16_swap_b32_e32 v76, v77
	v_max_f32_e32 v186, v186, v187
	v_max_f32_e32 v76, v76, v77
	v_mov_b32_e32 v187, v186
	v_mov_b32_e32 v77, v76
	s_nop 1
	s_nop 1
	v_permlane32_swap_b32_e32 v186, v187
	v_permlane32_swap_b32_e32 v76, v77
	v_max_f32_e32 v186, v186, v187
	v_max_f32_e32 v76, v76, v77
	v_fma_f32 v186, v186, s36, v188
	v_fma_f32 v76, v76, s36, v188
	v_max_f32_e32 v186, s29, v186
	v_max_f32_e32 v76, s29, v76
	v_cndmask_b32_e64 v186, v148, v186, s[44:45]
	v_cndmask_b32_e64 v76, v148, v76, s[42:43]
	v_max_f32_e32 v187, v160, v186
	v_max_f32_e32 v77, v161, v76
	v_sub_f32_e32 v248, v160, v187
	v_sub_f32_e32 v0, v161, v77
	v_exp_f32_e32 v236, v248
	v_exp_f32_e32 v0, v0
	v_cndmask_b32_e64 v186, v209, v187, s[44:45]
	v_cndmask_b32_e64 v76, v209, v77, s[42:43]
	v_mov_b32_e32 v160, v187
	v_mov_b32_e32 v161, v77
	v_sub_f32_e32 v246, v188, v186
	v_sub_f32_e32 v78, v188, v76
	v_pk_mul_f32 v[36:37], v[36:37], v[236:237] op_sel_hi:[1,0]
	v_pk_mul_f32 v[32:33], v[32:33], v[0:1] op_sel_hi:[1,0]
	v_pk_mul_f32 v[34:35], v[34:35], v[236:237] op_sel_hi:[1,0]
	v_pk_mul_f32 v[30:31], v[30:31], v[0:1] op_sel_hi:[1,0]
	v_pk_mul_f32 v[48:49], v[48:49], v[236:237] op_sel_hi:[1,0]
	v_pk_mul_f32 v[28:29], v[28:29], v[0:1] op_sel_hi:[1,0]
	v_pk_mul_f32 v[46:47], v[46:47], v[236:237] op_sel_hi:[1,0]
	v_pk_mul_f32 v[26:27], v[26:27], v[0:1] op_sel_hi:[1,0]
	v_pk_mul_f32 v[44:45], v[44:45], v[236:237] op_sel_hi:[1,0]
	v_pk_mul_f32 v[24:25], v[24:25], v[0:1] op_sel_hi:[1,0]
	v_pk_mul_f32 v[42:43], v[42:43], v[236:237] op_sel_hi:[1,0]
	v_pk_mul_f32 v[22:23], v[22:23], v[0:1] op_sel_hi:[1,0]
	v_pk_mul_f32 v[52:53], v[52:53], v[236:237] op_sel_hi:[1,0]
	v_pk_mul_f32 v[20:21], v[20:21], v[0:1] op_sel_hi:[1,0]
	v_pk_mul_f32 v[50:51], v[50:51], v[236:237] op_sel_hi:[1,0]
	v_pk_mul_f32 v[18:19], v[18:19], v[0:1] op_sel_hi:[1,0]
	v_pk_fma_f32 v[170:171], v[170:171], s[36:37], v[246:247] op_sel_hi:[1,0,0]
	v_pk_fma_f32 v[64:65], v[64:65], s[36:37], v[78:79] op_sel_hi:[1,0,0]
	v_pk_fma_f32 v[172:173], v[172:173], s[36:37], v[246:247] op_sel_hi:[1,0,0]
	v_pk_fma_f32 v[66:67], v[66:67], s[36:37], v[78:79] op_sel_hi:[1,0,0]
	v_pk_fma_f32 v[174:175], v[174:175], s[36:37], v[246:247] op_sel_hi:[1,0,0]
	v_pk_fma_f32 v[68:69], v[68:69], s[36:37], v[78:79] op_sel_hi:[1,0,0]
	v_pk_fma_f32 v[176:177], v[176:177], s[36:37], v[246:247] op_sel_hi:[1,0,0]
	v_pk_fma_f32 v[70:71], v[70:71], s[36:37], v[78:79] op_sel_hi:[1,0,0]
	v_pk_fma_f32 v[178:179], v[178:179], s[36:37], v[246:247] op_sel_hi:[1,0,0]
	v_pk_fma_f32 v[72:73], v[72:73], s[36:37], v[78:79] op_sel_hi:[1,0,0]
	v_pk_fma_f32 v[180:181], v[180:181], s[36:37], v[246:247] op_sel_hi:[1,0,0]
	v_pk_fma_f32 v[74:75], v[74:75], s[36:37], v[78:79] op_sel_hi:[1,0,0]
	v_pk_fma_f32 v[182:183], v[182:183], s[36:37], v[246:247] op_sel_hi:[1,0,0]
	v_pk_fma_f32 v[80:81], v[80:81], s[36:37], v[78:79] op_sel_hi:[1,0,0]
	v_pk_fma_f32 v[184:185], v[184:185], s[36:37], v[246:247] op_sel_hi:[1,0,0]
	v_pk_fma_f32 v[82:83], v[82:83], s[36:37], v[78:79] op_sel_hi:[1,0,0]
	v_exp_f32_e32 v170, v170
	v_exp_f32_e32 v64, v64
	v_exp_f32_e32 v171, v171
	v_exp_f32_e32 v65, v65
	v_exp_f32_e32 v172, v172
	v_exp_f32_e32 v66, v66
	v_exp_f32_e32 v173, v173
	v_exp_f32_e32 v67, v67
	v_exp_f32_e32 v174, v174
	v_exp_f32_e32 v68, v68
	v_exp_f32_e32 v175, v175
	v_exp_f32_e32 v69, v69
	v_exp_f32_e32 v176, v176
	v_exp_f32_e32 v70, v70
	v_exp_f32_e32 v177, v177
	v_exp_f32_e32 v71, v71
	v_exp_f32_e32 v178, v178
	v_exp_f32_e32 v72, v72
	v_exp_f32_e32 v179, v179
	v_exp_f32_e32 v73, v73
	v_exp_f32_e32 v180, v180
	v_exp_f32_e32 v74, v74
	v_exp_f32_e32 v181, v181
	v_exp_f32_e32 v75, v75
	v_exp_f32_e32 v182, v182
	v_exp_f32_e32 v80, v80
	v_exp_f32_e32 v183, v183
	v_exp_f32_e32 v81, v81
	v_exp_f32_e32 v184, v184
	v_exp_f32_e32 v82, v82
	v_exp_f32_e32 v185, v185
	v_exp_f32_e32 v83, v83
	s_nop 0
	s_nop 0
	v_pk_add_f32 v[238:239], v[170:171], v[172:173]
	v_pk_add_f32 v[84:85], v[64:65], v[66:67]
	v_pk_add_f32 v[240:241], v[174:175], v[176:177]
	v_pk_add_f32 v[86:87], v[68:69], v[70:71]
	v_pk_add_f32 v[242:243], v[178:179], v[180:181]
	v_pk_add_f32 v[76:77], v[72:73], v[74:75]
	v_pk_add_f32 v[244:245], v[182:183], v[184:185]
	v_pk_add_f32 v[78:79], v[80:81], v[82:83]
	v_pk_add_f32 v[238:239], v[238:239], v[240:241]
	v_pk_add_f32 v[84:85], v[84:85], v[86:87]
	v_pk_add_f32 v[242:243], v[242:243], v[244:245]
	v_pk_add_f32 v[76:77], v[76:77], v[78:79]
	s_nop 0
	s_nop 0
	v_pk_add_f32 v[238:239], v[238:239], v[242:243]
	v_pk_add_f32 v[84:85], v[84:85], v[76:77]
	s_nop 0
	s_nop 0
	v_add_f32_e32 v238, v238, v239
	v_add_f32_e32 v84, v84, v85
	v_fma_f32 v144, v144, v236, v238
	v_fma_f32 v145, v145, v0, v84
	v_cvt_pk_bf16_f32 v58, v170, v171
	v_cvt_pk_bf16_f32 v67, v66, v67
	v_cvt_pk_bf16_f32 v59, v172, v173
	v_cvt_pk_bf16_f32 v66, v64, v65
	v_cvt_pk_bf16_f32 v60, v174, v175
	v_cvt_pk_bf16_f32 v68, v68, v69
	v_cvt_pk_bf16_f32 v61, v176, v177
	v_cvt_pk_bf16_f32 v69, v70, v71
	v_cvt_pk_bf16_f32 v54, v178, v179
	v_cvt_pk_bf16_f32 v62, v72, v73
	v_cvt_pk_bf16_f32 v55, v180, v181
	v_cvt_pk_bf16_f32 v63, v74, v75
	v_cvt_pk_bf16_f32 v56, v182, v183
	v_cvt_pk_bf16_f32 v64, v80, v81
	v_cvt_pk_bf16_f32 v57, v184, v185
	v_cvt_pk_bf16_f32 v65, v82, v83
	s_branch .LBB0_446
.Lp2v_only0:
	s_setprio 1
	v_mfma_f32_16x16x32_bf16 v[170:173], v[64:67], v[2:5], 0
	v_mfma_f32_16x16x32_bf16 v[174:177], v[68:71], v[2:5], 0
	v_mfma_f32_16x16x32_bf16 v[170:173], v[54:57], v[6:9], v[170:173]
	v_mfma_f32_16x16x32_bf16 v[178:181], v[72:75], v[2:5], 0
	v_mfma_f32_16x16x32_bf16 v[174:177], v[58:61], v[6:9], v[174:177]
	v_mfma_f32_16x16x32_bf16 v[182:185], v[80:83], v[2:5], 0
	v_mfma_f32_16x16x32_bf16 v[178:181], v[76:79], v[6:9], v[178:181]
	v_mfma_f32_16x16x32_bf16 v[182:185], v[84:87], v[6:9], v[182:185]
	s_setprio 0
	s_nop 7
	s_nop 7
	v_max3_f32 v186, v170, v171, v172
	v_max3_f32 v186, v186, v173, v174
	v_max3_f32 v186, v186, v175, v176
	v_max3_f32 v186, v186, v177, v178
	v_max3_f32 v186, v186, v179, v180
	v_max3_f32 v186, v186, v181, v182
	v_max3_f32 v186, v186, v183, v184
	v_max_f32_e32 v186, v186, v185
	v_mov_b32_e32 v187, v186
	s_nop 1
	v_permlane16_swap_b32_e32 v186, v187
	v_max_f32_e32 v186, v186, v187
	v_mov_b32_e32 v187, v186
	s_nop 1
	v_permlane32_swap_b32_e32 v186, v187
	v_max_f32_e32 v186, v186, v187
	v_fma_f32 v186, v186, s36, v188
	v_max_f32_e32 v186, s29, v186
	v_cndmask_b32_e64 v186, v148, v186, s[44:45]
	v_max_f32_e32 v187, v160, v186
	v_sub_f32_e32 v248, v160, v187
	v_exp_f32_e32 v236, v248
	v_cndmask_b32_e64 v186, v209, v187, s[44:45]
	v_mov_b32_e32 v160, v187
	v_sub_f32_e32 v246, v188, v186
	v_pk_mul_f32 v[36:37], v[36:37], v[236:237] op_sel_hi:[1,0]
	v_pk_mul_f32 v[34:35], v[34:35], v[236:237] op_sel_hi:[1,0]
	v_pk_mul_f32 v[48:49], v[48:49], v[236:237] op_sel_hi:[1,0]
	v_pk_mul_f32 v[46:47], v[46:47], v[236:237] op_sel_hi:[1,0]
	v_pk_mul_f32 v[44:45], v[44:45], v[236:237] op_sel_hi:[1,0]
	v_pk_mul_f32 v[42:43], v[42:43], v[236:237] op_sel_hi:[1,0]
	v_pk_mul_f32 v[52:53], v[52:53], v[236:237] op_sel_hi:[1,0]
	v_pk_mul_f32 v[50:51], v[50:51], v[236:237] op_sel_hi:[1,0]
	v_pk_fma_f32 v[170:171], v[170:171], s[36:37], v[246:247] op_sel_hi:[1,0,0]
	v_pk_fma_f32 v[172:173], v[172:173], s[36:37], v[246:247] op_sel_hi:[1,0,0]
	v_pk_fma_f32 v[174:175], v[174:175], s[36:37], v[246:247] op_sel_hi:[1,0,0]
	v_pk_fma_f32 v[176:177], v[176:177], s[36:37], v[246:247] op_sel_hi:[1,0,0]
	v_pk_fma_f32 v[178:179], v[178:179], s[36:37], v[246:247] op_sel_hi:[1,0,0]
	v_pk_fma_f32 v[180:181], v[180:181], s[36:37], v[246:247] op_sel_hi:[1,0,0]
	v_pk_fma_f32 v[182:183], v[182:183], s[36:37], v[246:247] op_sel_hi:[1,0,0]
	v_pk_fma_f32 v[184:185], v[184:185], s[36:37], v[246:247] op_sel_hi:[1,0,0]
	v_exp_f32_e32 v170, v170
	v_exp_f32_e32 v171, v171
	v_exp_f32_e32 v172, v172
	v_exp_f32_e32 v173, v173
	v_exp_f32_e32 v174, v174
	v_exp_f32_e32 v175, v175
	v_exp_f32_e32 v176, v176
	v_exp_f32_e32 v177, v177
	v_exp_f32_e32 v178, v178
	v_exp_f32_e32 v179, v179
	v_exp_f32_e32 v180, v180
	v_exp_f32_e32 v181, v181
	v_exp_f32_e32 v182, v182
	v_exp_f32_e32 v183, v183
	v_exp_f32_e32 v184, v184
	v_exp_f32_e32 v185, v185
	s_nop 0
	v_pk_add_f32 v[238:239], v[170:171], v[172:173]
	v_pk_add_f32 v[240:241], v[174:175], v[176:177]
	v_pk_add_f32 v[242:243], v[178:179], v[180:181]
	v_pk_add_f32 v[244:245], v[182:183], v[184:185]
	v_pk_add_f32 v[238:239], v[238:239], v[240:241]
	v_pk_add_f32 v[242:243], v[242:243], v[244:245]
	s_nop 0
	v_pk_add_f32 v[238:239], v[238:239], v[242:243]
	s_nop 0
	v_add_f32_e32 v238, v238, v239
	v_fma_f32 v144, v144, v236, v238
	v_cvt_pk_bf16_f32 v58, v170, v171
	v_cvt_pk_bf16_f32 v59, v172, v173
	v_cvt_pk_bf16_f32 v60, v174, v175
	v_cvt_pk_bf16_f32 v61, v176, v177
	v_cvt_pk_bf16_f32 v54, v178, v179
	v_cvt_pk_bf16_f32 v55, v180, v181
	v_cvt_pk_bf16_f32 v56, v182, v183
	v_cvt_pk_bf16_f32 v57, v184, v185
	s_branch .LBB0_445
.Lp2v_m1:
	s_setprio 1
	v_mfma_f32_16x16x32_bf16 v[64:67], v[64:67], v[10:13], 0
	v_mfma_f32_16x16x32_bf16 v[68:71], v[68:71], v[10:13], 0
	v_mfma_f32_16x16x32_bf16 v[64:67], v[54:57], v[14:17], v[64:67]
	v_mfma_f32_16x16x32_bf16 v[72:75], v[72:75], v[10:13], 0
	v_mfma_f32_16x16x32_bf16 v[68:71], v[58:61], v[14:17], v[68:71]
	v_mfma_f32_16x16x32_bf16 v[80:83], v[80:83], v[10:13], 0
	v_mfma_f32_16x16x32_bf16 v[72:75], v[76:79], v[14:17], v[72:75]
	v_mfma_f32_16x16x32_bf16 v[80:83], v[84:87], v[14:17], v[80:83]
	s_setprio 0
	s_nop 7
	s_nop 7
	v_mov_b32_e32 v54, 0
	v_mov_b32_e32 v55, v54
	v_mov_b32_e32 v56, v54
	v_mov_b32_e32 v57, v54
	v_mov_b32_e32 v58, v54
	v_mov_b32_e32 v59, v54
	v_mov_b32_e32 v60, v54
	v_mov_b32_e32 v61, v54
	v_max3_f32 v76, v64, v65, v66
	v_max3_f32 v76, v76, v67, v68
	v_max3_f32 v76, v76, v69, v70
	v_max3_f32 v76, v76, v71, v72
	v_max3_f32 v76, v76, v73, v74
	v_max3_f32 v76, v76, v75, v80
	v_max3_f32 v76, v76, v81, v82
	v_max_f32_e32 v76, v76, v83
	v_mov_b32_e32 v77, v76
	s_nop 1
	v_permlane16_swap_b32_e32 v76, v77
	v_max_f32_e32 v76, v76, v77
	v_mov_b32_e32 v77, v76
	s_nop 1
	v_permlane32_swap_b32_e32 v76, v77
	v_max_f32_e32 v76, v76, v77
	v_fma_f32 v76, v76, s36, v188
	v_max_f32_e32 v76, s29, v76
	v_cndmask_b32_e64 v76, v148, v76, s[42:43]
	v_max_f32_e32 v77, v161, v76
	v_sub_f32_e32 v0, v161, v77
	v_exp_f32_e32 v0, v0
	v_cndmask_b32_e64 v76, v209, v77, s[42:43]
	v_mov_b32_e32 v161, v77
	v_sub_f32_e32 v78, v188, v76
	v_pk_mul_f32 v[32:33], v[32:33], v[0:1] op_sel_hi:[1,0]
	v_pk_mul_f32 v[30:31], v[30:31], v[0:1] op_sel_hi:[1,0]
	v_pk_mul_f32 v[28:29], v[28:29], v[0:1] op_sel_hi:[1,0]
	v_pk_mul_f32 v[26:27], v[26:27], v[0:1] op_sel_hi:[1,0]
	v_pk_mul_f32 v[24:25], v[24:25], v[0:1] op_sel_hi:[1,0]
	v_pk_mul_f32 v[22:23], v[22:23], v[0:1] op_sel_hi:[1,0]
	v_pk_mul_f32 v[20:21], v[20:21], v[0:1] op_sel_hi:[1,0]
	v_pk_mul_f32 v[18:19], v[18:19], v[0:1] op_sel_hi:[1,0]
	v_pk_fma_f32 v[64:65], v[64:65], s[36:37], v[78:79] op_sel_hi:[1,0,0]
	v_pk_fma_f32 v[66:67], v[66:67], s[36:37], v[78:79] op_sel_hi:[1,0,0]
	v_pk_fma_f32 v[68:69], v[68:69], s[36:37], v[78:79] op_sel_hi:[1,0,0]
	v_pk_fma_f32 v[70:71], v[70:71], s[36:37], v[78:79] op_sel_hi:[1,0,0]
	v_pk_fma_f32 v[72:73], v[72:73], s[36:37], v[78:79] op_sel_hi:[1,0,0]
	v_pk_fma_f32 v[74:75], v[74:75], s[36:37], v[78:79] op_sel_hi:[1,0,0]
	v_pk_fma_f32 v[80:81], v[80:81], s[36:37], v[78:79] op_sel_hi:[1,0,0]
	v_pk_fma_f32 v[82:83], v[82:83], s[36:37], v[78:79] op_sel_hi:[1,0,0]
	v_exp_f32_e32 v64, v64
	v_exp_f32_e32 v65, v65
	v_exp_f32_e32 v66, v66
	v_exp_f32_e32 v67, v67
	v_exp_f32_e32 v68, v68
	v_exp_f32_e32 v69, v69
	v_exp_f32_e32 v70, v70
	v_exp_f32_e32 v71, v71
	v_exp_f32_e32 v72, v72
	v_exp_f32_e32 v73, v73
	v_exp_f32_e32 v74, v74
	v_exp_f32_e32 v75, v75
	v_exp_f32_e32 v80, v80
	v_exp_f32_e32 v81, v81
	v_exp_f32_e32 v82, v82
	v_exp_f32_e32 v83, v83
	s_nop 0
	v_pk_add_f32 v[84:85], v[64:65], v[66:67]
	v_pk_add_f32 v[86:87], v[68:69], v[70:71]
	v_pk_add_f32 v[76:77], v[72:73], v[74:75]
	v_pk_add_f32 v[78:79], v[80:81], v[82:83]
	v_pk_add_f32 v[84:85], v[84:85], v[86:87]
	v_pk_add_f32 v[76:77], v[76:77], v[78:79]
	s_nop 0
	v_pk_add_f32 v[84:85], v[84:85], v[76:77]
	s_nop 0
	v_add_f32_e32 v84, v84, v85
	v_fma_f32 v145, v145, v0, v84
	v_cvt_pk_bf16_f32 v67, v66, v67
	v_cvt_pk_bf16_f32 v66, v64, v65
	v_cvt_pk_bf16_f32 v68, v68, v69
	v_cvt_pk_bf16_f32 v69, v70, v71
	v_cvt_pk_bf16_f32 v62, v72, v73
	v_cvt_pk_bf16_f32 v63, v74, v75
	v_cvt_pk_bf16_f32 v64, v80, v81
	v_cvt_pk_bf16_f32 v65, v82, v83
	s_branch .LBB0_446
